# top-k bisection counting pass: per-lane sorted 16/8-word blocks (Batcher network once per row) + binary-search count via v_cndmask trees, 5 compares per 16 words instead of 16
# speedup vs baseline: 1.3178x; 1.0339x over previous
.LBB0_890:
	s_or_b64 exec, exec, s[0:1]
	v_readlane_b32 s0, v254, 51
	v_readlane_b32 s4, v254, 29
	s_lshl_b32 s0, s0, 8
	v_readlane_b32 s18, v254, 43
	v_and_b32_e32 v16, 63, v43
	v_readlane_b32 s1, v254, 52
	v_readlane_b32 s19, v254, 44
	s_add_u32 s0, s18, s0
	v_ashrrev_i32_e32 v43, 31, v42
	s_addc_u32 s1, s19, 0
	v_mul_u32_u24_e32 v2, 0x4100, v47
	v_lshlrev_b64 v[0:1], 8, v[42:43]
	v_lshlrev_b32_e32 v3, 2, v16
	v_lshl_add_u64 v[0:1], s[0:1], 0, v[0:1]
	s_cmpk_lt_u32 s71, 0xc00
	s_waitcnt vmcnt(3)
	v_add3_u32 v28, v46, v2, v3
	v_readlane_b32 s5, v254, 30
	v_readlane_b32 s6, v254, 31
	v_readlane_b32 s7, v254, 32
	v_readlane_b32 s8, v254, 33
	v_readlane_b32 s9, v254, 34
	v_readlane_b32 s10, v254, 35
	v_readlane_b32 s11, v254, 36
	v_readlane_b32 s12, v254, 37
	v_readlane_b32 s13, v254, 38
	v_readlane_b32 s14, v254, 39
	v_readlane_b32 s15, v254, 40
	v_readlane_b32 s16, v254, 41
	v_readlane_b32 s17, v254, 42
	s_waitcnt lgkmcnt(0)
	s_barrier
	s_cbranch_scc0 .LBB0_1038
	s_cmpk_lt_u32 s71, 0x800
	s_cbranch_scc0 .LBB0_1043
	s_cmpk_lt_u32 s71, 0x400
	s_cbranch_scc0 .LBB0_1044
	ds_read2st64_b32 v[26:27], v28 offset1:1
	ds_read2st64_b32 v[24:25], v28 offset0:2 offset1:3
	ds_read2st64_b32 v[22:23], v28 offset0:4 offset1:5
	ds_read2st64_b32 v[20:21], v28 offset0:6 offset1:7
	ds_read2st64_b32 v[18:19], v28 offset0:8 offset1:9
	ds_read2st64_b32 v[14:15], v28 offset0:10 offset1:11
	ds_read2st64_b32 v[12:13], v28 offset0:12 offset1:13
	ds_read2st64_b32 v[10:11], v28 offset0:14 offset1:15
	ds_read2st64_b32 v[8:9], v28 offset0:16 offset1:17
	ds_read2st64_b32 v[6:7], v28 offset0:18 offset1:19
	ds_read2st64_b32 v[4:5], v28 offset0:20 offset1:21
	ds_read2st64_b32 v[2:3], v28 offset0:22 offset1:23
	v_or_b32_e32 v29, 0x600, v16
	v_cmp_gt_u32_e32 vcc, s72, v29
	s_waitcnt vmcnt(1)
	v_mov_b32_e32 v36, 0
	v_mov_b32_e32 v37, 0
	s_and_saveexec_b64 s[0:1], vcc
	ds_read_b32 v37, v28 offset:6144
	s_or_b64 exec, exec, s[0:1]
	v_or_b32_e32 v29, 0x640, v16
	v_cmp_gt_u32_e32 vcc, s72, v29
	s_and_saveexec_b64 s[0:1], vcc
	ds_read_b32 v36, v28 offset:6400
	s_or_b64 exec, exec, s[0:1]
	v_or_b32_e32 v29, 0x680, v16
	v_cmp_gt_u32_e32 vcc, s72, v29
	v_mov_b32_e32 v34, 0
	v_mov_b32_e32 v35, 0
	s_and_saveexec_b64 s[0:1], vcc
	ds_read_b32 v35, v28 offset:6656
	s_or_b64 exec, exec, s[0:1]
	v_or_b32_e32 v29, 0x6c0, v16
	v_cmp_gt_u32_e32 vcc, s72, v29
	s_and_saveexec_b64 s[0:1], vcc
	ds_read_b32 v34, v28 offset:6912
	s_or_b64 exec, exec, s[0:1]
	v_or_b32_e32 v29, 0x700, v16
	v_cmp_gt_u32_e32 vcc, s72, v29
	v_mov_b32_e32 v32, 0
	v_mov_b32_e32 v33, 0
	s_and_saveexec_b64 s[0:1], vcc
	ds_read_b32 v33, v28 offset:7168
	s_or_b64 exec, exec, s[0:1]
	v_or_b32_e32 v29, 0x740, v16
	v_cmp_gt_u32_e32 vcc, s72, v29
	s_and_saveexec_b64 s[0:1], vcc
	ds_read_b32 v32, v28 offset:7424
	s_or_b64 exec, exec, s[0:1]
	v_or_b32_e32 v29, 0x780, v16
	v_cmp_gt_u32_e32 vcc, s72, v29
	v_mov_b32_e32 v29, 0
	v_mov_b32_e32 v31, 0
	s_and_saveexec_b64 s[0:1], vcc
	ds_read_b32 v31, v28 offset:7680
	s_or_b64 exec, exec, s[0:1]
	v_or_b32_e32 v30, 0x7c0, v16
	v_cmp_gt_u32_e32 vcc, s72, v30
	s_and_saveexec_b64 s[0:1], vcc
	ds_read_b32 v29, v28 offset:7936
	s_or_b64 exec, exec, s[0:1]
	s_waitcnt vmcnt(0)
	v_mov_b32_e32 v38, 31
	v_mov_b32_e32 v30, 0
	s_waitcnt lgkmcnt(0)
	s_waitcnt vmcnt(0)
	v_max_u32_e32 v138, v26, v18
	v_min_u32_e32 v139, v26, v18
	v_max_u32_e32 v140, v27, v19
	v_min_u32_e32 v141, v27, v19
	v_max_u32_e32 v142, v24, v14
	v_min_u32_e32 v143, v24, v14
	v_max_u32_e32 v144, v25, v15
	v_min_u32_e32 v145, v25, v15
	v_max_u32_e32 v146, v22, v12
	v_min_u32_e32 v147, v22, v12
	v_max_u32_e32 v148, v23, v13
	v_min_u32_e32 v149, v23, v13
	v_max_u32_e32 v150, v20, v10
	v_min_u32_e32 v151, v20, v10
	v_max_u32_e32 v152, v21, v11
	v_min_u32_e32 v153, v21, v11
	v_max_u32_e32 v154, v138, v146
	v_min_u32_e32 v155, v138, v146
	v_max_u32_e32 v146, v140, v148
	v_min_u32_e32 v138, v140, v148
	v_max_u32_e32 v148, v142, v150
	v_min_u32_e32 v140, v142, v150
	v_max_u32_e32 v150, v144, v152
	v_min_u32_e32 v142, v144, v152
	v_max_u32_e32 v152, v139, v147
	v_min_u32_e32 v144, v139, v147
	v_max_u32_e32 v147, v141, v149
	v_min_u32_e32 v139, v141, v149
	v_max_u32_e32 v149, v143, v151
	v_min_u32_e32 v141, v143, v151
	v_max_u32_e32 v151, v145, v153
	v_min_u32_e32 v143, v145, v153
	v_max_u32_e32 v153, v155, v152
	v_min_u32_e32 v145, v155, v152
	v_max_u32_e32 v152, v138, v147
	v_min_u32_e32 v155, v138, v147
	v_max_u32_e32 v147, v140, v149
	v_min_u32_e32 v138, v140, v149
	v_max_u32_e32 v149, v142, v151
	v_min_u32_e32 v140, v142, v151
	v_max_u32_e32 v151, v154, v148
	v_min_u32_e32 v142, v154, v148
	v_max_u32_e32 v148, v146, v150
	v_min_u32_e32 v154, v146, v150
	v_max_u32_e32 v150, v153, v147
	v_min_u32_e32 v146, v153, v147
	v_max_u32_e32 v147, v152, v149
	v_min_u32_e32 v153, v152, v149
	v_max_u32_e32 v149, v145, v138
	v_min_u32_e32 v152, v145, v138
	v_max_u32_e32 v138, v155, v140
	v_min_u32_e32 v145, v155, v140
	v_max_u32_e32 v140, v144, v141
	v_min_u32_e32 v155, v144, v141
	v_max_u32_e32 v141, v139, v143
	v_min_u32_e32 v144, v139, v143
	v_max_u32_e32 v143, v142, v149
	v_min_u32_e32 v139, v142, v149
	v_max_u32_e32 v149, v154, v138
	v_min_u32_e32 v142, v154, v138
	v_max_u32_e32 v138, v146, v140
	v_min_u32_e32 v154, v146, v140
	v_max_u32_e32 v140, v153, v141
	v_min_u32_e32 v146, v153, v141
	v_max_u32_e32 v141, v143, v150
	v_min_u32_e32 v153, v143, v150
	v_max_u32_e32 v150, v149, v147
	v_min_u32_e32 v143, v149, v147
	v_max_u32_e32 v147, v138, v139
	v_min_u32_e32 v149, v138, v139
	v_max_u32_e32 v139, v140, v142
	v_min_u32_e32 v138, v140, v142
	v_max_u32_e32 v142, v152, v154
	v_min_u32_e32 v140, v152, v154
	v_max_u32_e32 v154, v145, v146
	v_min_u32_e32 v152, v145, v146
	v_max_u32_e32 v146, v151, v148
	v_min_u32_e32 v145, v151, v148
	v_max_u32_e32 v148, v141, v150
	v_min_u32_e32 v151, v141, v150
	v_max_u32_e32 v150, v153, v143
	v_min_u32_e32 v141, v153, v143
	v_max_u32_e32 v143, v147, v139
	v_min_u32_e32 v153, v147, v139
	v_max_u32_e32 v139, v149, v138
	v_min_u32_e32 v147, v149, v138
	v_max_u32_e32 v138, v142, v154
	v_min_u32_e32 v149, v142, v154
	v_max_u32_e32 v154, v140, v152
	v_min_u32_e32 v142, v140, v152
	v_max_u32_e32 v152, v155, v144
	v_min_u32_e32 v140, v155, v144
	v_max_u32_e32 v144, v145, v139
	v_min_u32_e32 v155, v145, v139
	v_max_u32_e32 v139, v151, v138
	v_min_u32_e32 v145, v151, v138
	v_max_u32_e32 v138, v141, v154
	v_min_u32_e32 v151, v141, v154
	v_max_u32_e32 v154, v153, v152
	v_min_u32_e32 v141, v153, v152
	v_max_u32_e32 v152, v144, v150
	v_min_u32_e32 v153, v144, v150
	v_max_u32_e32 v150, v139, v143
	v_min_u32_e32 v144, v139, v143
	v_max_u32_e32 v143, v138, v155
	v_min_u32_e32 v139, v138, v155
	v_max_u32_e32 v155, v154, v145
	v_min_u32_e32 v138, v154, v145
	v_max_u32_e32 v145, v147, v151
	v_min_u32_e32 v154, v147, v151
	v_max_u32_e32 v151, v149, v141
	v_min_u32_e32 v147, v149, v141
	v_max_u32_e32 v141, v152, v148
	v_min_u32_e32 v149, v152, v148
	v_max_u32_e32 v148, v150, v153
	v_min_u32_e32 v152, v150, v153
	v_max_u32_e32 v153, v143, v144
	v_min_u32_e32 v150, v143, v144
	v_max_u32_e32 v144, v155, v139
	v_min_u32_e32 v143, v155, v139
	v_max_u32_e32 v139, v145, v138
	v_min_u32_e32 v155, v145, v138
	v_max_u32_e32 v138, v151, v154
	v_min_u32_e32 v145, v151, v154
	v_max_u32_e32 v154, v142, v147
	v_min_u32_e32 v151, v142, v147
	v_max_u32_e32 v147, v8, v37
	v_min_u32_e32 v142, v8, v37
	v_max_u32_e32 v156, v9, v36
	v_min_u32_e32 v157, v9, v36
	v_max_u32_e32 v158, v6, v35
	v_min_u32_e32 v159, v6, v35
	v_max_u32_e32 v160, v7, v34
	v_min_u32_e32 v161, v7, v34
	v_max_u32_e32 v162, v4, v33
	v_min_u32_e32 v163, v4, v33
	v_max_u32_e32 v164, v5, v32
	v_min_u32_e32 v165, v5, v32
	v_max_u32_e32 v166, v2, v31
	v_min_u32_e32 v167, v2, v31
	v_max_u32_e32 v168, v3, v29
	v_min_u32_e32 v169, v3, v29
	v_max_u32_e32 v170, v147, v162
	v_min_u32_e32 v171, v147, v162
	v_max_u32_e32 v162, v156, v164
	v_min_u32_e32 v147, v156, v164
	v_max_u32_e32 v164, v158, v166
	v_min_u32_e32 v156, v158, v166
	v_max_u32_e32 v166, v160, v168
	v_min_u32_e32 v158, v160, v168
	v_max_u32_e32 v168, v142, v163
	v_min_u32_e32 v160, v142, v163
	v_max_u32_e32 v163, v157, v165
	v_min_u32_e32 v142, v157, v165
	v_max_u32_e32 v165, v159, v167
	v_min_u32_e32 v157, v159, v167
	v_max_u32_e32 v167, v161, v169
	v_min_u32_e32 v159, v161, v169
	v_max_u32_e32 v169, v171, v168
	v_min_u32_e32 v161, v171, v168
	v_max_u32_e32 v168, v147, v163
	v_min_u32_e32 v171, v147, v163
	v_max_u32_e32 v163, v156, v165
	v_min_u32_e32 v147, v156, v165
	v_max_u32_e32 v165, v158, v167
	v_min_u32_e32 v156, v158, v167
	v_max_u32_e32 v167, v170, v164
	v_min_u32_e32 v158, v170, v164
	v_max_u32_e32 v164, v162, v166
	v_min_u32_e32 v170, v162, v166
	v_max_u32_e32 v166, v169, v163
	v_min_u32_e32 v162, v169, v163
	v_max_u32_e32 v163, v168, v165
	v_min_u32_e32 v169, v168, v165
	v_max_u32_e32 v165, v161, v147
	v_min_u32_e32 v168, v161, v147
	v_max_u32_e32 v147, v171, v156
	v_min_u32_e32 v161, v171, v156
	v_max_u32_e32 v156, v160, v157
	v_min_u32_e32 v171, v160, v157
	v_max_u32_e32 v157, v142, v159
	v_min_u32_e32 v160, v142, v159
	v_max_u32_e32 v159, v158, v165
	v_min_u32_e32 v142, v158, v165
	v_max_u32_e32 v165, v170, v147
	v_min_u32_e32 v158, v170, v147
	v_max_u32_e32 v147, v162, v156
	v_min_u32_e32 v170, v162, v156
	v_max_u32_e32 v156, v169, v157
	v_min_u32_e32 v162, v169, v157
	v_max_u32_e32 v157, v159, v166
	v_min_u32_e32 v169, v159, v166
	v_max_u32_e32 v166, v165, v163
	v_min_u32_e32 v159, v165, v163
	v_max_u32_e32 v163, v147, v142
	v_min_u32_e32 v165, v147, v142
	v_max_u32_e32 v142, v156, v158
	v_min_u32_e32 v147, v156, v158
	v_max_u32_e32 v158, v168, v170
	v_min_u32_e32 v156, v168, v170
	v_max_u32_e32 v170, v161, v162
	v_min_u32_e32 v168, v161, v162
	v_max_u32_e32 v162, v167, v164
	v_min_u32_e32 v161, v167, v164
	v_max_u32_e32 v164, v157, v166
	v_min_u32_e32 v167, v157, v166
	v_max_u32_e32 v166, v169, v159
	v_min_u32_e32 v157, v169, v159
	v_max_u32_e32 v159, v163, v142
	v_min_u32_e32 v169, v163, v142
	v_max_u32_e32 v142, v165, v147
	v_min_u32_e32 v163, v165, v147
	v_max_u32_e32 v147, v158, v170
	v_min_u32_e32 v165, v158, v170
	v_max_u32_e32 v170, v156, v168
	v_min_u32_e32 v158, v156, v168
	v_max_u32_e32 v168, v171, v160
	v_min_u32_e32 v156, v171, v160
	v_max_u32_e32 v160, v161, v142
	v_min_u32_e32 v171, v161, v142
	v_max_u32_e32 v142, v167, v147
	v_min_u32_e32 v161, v167, v147
	v_max_u32_e32 v147, v157, v170
	v_min_u32_e32 v167, v157, v170
	v_max_u32_e32 v170, v169, v168
	v_min_u32_e32 v157, v169, v168
	v_max_u32_e32 v168, v160, v166
	v_min_u32_e32 v169, v160, v166
	v_max_u32_e32 v166, v142, v159
	v_min_u32_e32 v160, v142, v159
	v_max_u32_e32 v159, v147, v171
	v_min_u32_e32 v142, v147, v171
	v_max_u32_e32 v171, v170, v161
	v_min_u32_e32 v147, v170, v161
	v_max_u32_e32 v161, v163, v167
	v_min_u32_e32 v170, v163, v167
	v_max_u32_e32 v167, v165, v157
	v_min_u32_e32 v163, v165, v157
	v_max_u32_e32 v157, v168, v164
	v_min_u32_e32 v165, v168, v164
	v_max_u32_e32 v164, v166, v169
	v_min_u32_e32 v168, v166, v169
	v_max_u32_e32 v169, v159, v160
	v_min_u32_e32 v166, v159, v160
	v_max_u32_e32 v160, v171, v142
	v_min_u32_e32 v159, v171, v142
	v_max_u32_e32 v142, v161, v147
	v_min_u32_e32 v171, v161, v147
	v_max_u32_e32 v147, v167, v170
	v_min_u32_e32 v161, v167, v170
	v_max_u32_e32 v170, v158, v163
	v_min_u32_e32 v167, v158, v163
.LBB0_910:
	v_lshlrev_b32_e64 v39, v38, 1
	v_or_b32_e32 v39, v39, v30
	v_cmp_ge_u32_e64 s[8:9], v144, v39
	v_cmp_ge_u32_e64 s[68:69], v140, v39
	s_nop 0
	v_cndmask_b32_e64 v134, v148, v138, s[8:9]
	v_cmp_ge_u32_e64 s[10:11], v134, v39
	s_nop 1
	v_cndmask_b32_e64 v134, v141, v153, s[10:11]
	v_cndmask_b32_e64 v135, v139, v154, s[10:11]
	v_cndmask_b32_e64 v134, v134, v135, s[8:9]
	v_cmp_ge_u32_e64 s[64:65], v134, v39
	s_nop 1
	v_cndmask_b32_e64 v134, v146, v149, s[64:65]
	v_cndmask_b32_e64 v135, v152, v150, s[64:65]
	v_cndmask_b32_e64 v136, v143, v155, s[64:65]
	v_cndmask_b32_e64 v137, v145, v151, s[64:65]
	v_cndmask_b32_e64 v134, v134, v135, s[10:11]
	v_cndmask_b32_e64 v136, v136, v137, s[10:11]
	v_cndmask_b32_e64 v134, v134, v136, s[8:9]
	v_cmp_ge_u32_e64 s[66:67], v134, v39
	s_bcnt1_i32_b64 s1, s[8:9]
	s_mov_b32 s0, s1
	s_bcnt1_i32_b64 s1, s[10:11]
	s_lshl1_add_u32 s0, s0, s1
	s_bcnt1_i32_b64 s1, s[64:65]
	s_lshl1_add_u32 s0, s0, s1
	s_bcnt1_i32_b64 s1, s[66:67]
	s_lshl1_add_u32 s0, s0, s1
	s_bcnt1_i32_b64 s1, s[68:69]
	s_add_i32 s0, s0, s1
	s_mov_b32 s2, s0
	v_cmp_ge_u32_e64 s[8:9], v160, v39
	v_cmp_ge_u32_e64 s[68:69], v156, v39
	s_nop 0
	v_cndmask_b32_e64 v134, v164, v147, s[8:9]
	v_cmp_ge_u32_e64 s[10:11], v134, v39
	s_nop 1
	v_cndmask_b32_e64 v134, v157, v169, s[10:11]
	v_cndmask_b32_e64 v135, v142, v170, s[10:11]
	v_cndmask_b32_e64 v134, v134, v135, s[8:9]
	v_cmp_ge_u32_e64 s[64:65], v134, v39
	s_nop 1
	v_cndmask_b32_e64 v134, v162, v165, s[64:65]
	v_cndmask_b32_e64 v135, v168, v166, s[64:65]
	v_cndmask_b32_e64 v136, v159, v171, s[64:65]
	v_cndmask_b32_e64 v137, v161, v167, s[64:65]
	v_cndmask_b32_e64 v134, v134, v135, s[10:11]
	v_cndmask_b32_e64 v136, v136, v137, s[10:11]
	v_cndmask_b32_e64 v134, v134, v136, s[8:9]
	v_cmp_ge_u32_e64 s[66:67], v134, v39
	s_bcnt1_i32_b64 s1, s[8:9]
	s_mov_b32 s0, s1
	s_bcnt1_i32_b64 s1, s[10:11]
	s_lshl1_add_u32 s0, s0, s1
	s_bcnt1_i32_b64 s1, s[64:65]
	s_lshl1_add_u32 s0, s0, s1
	s_bcnt1_i32_b64 s1, s[66:67]
	s_lshl1_add_u32 s0, s0, s1
	s_bcnt1_i32_b64 s1, s[68:69]
	s_add_i32 s0, s0, s1
	s_add_i32 s2, s2, s0
	s_cmpk_eq_i32 s2, 0x100
	s_cselect_b64 s[0:1], -1, 0
	s_cmpk_lt_u32 s2, 0x100
	s_cselect_b64 vcc, -1, 0
	v_cndmask_b32_e32 v30, v39, v30, vcc
	v_subrev_co_u32_e32 v38, vcc, 1, v38
	s_or_b64 s[0:1], s[0:1], vcc
	s_andn2_b64 vcc, exec, s[0:1]
	s_cbranch_vccnz .LBB0_910
	s_cmpk_eq_i32 s2, 0x100
	s_cbranch_scc1 .Lselfast_32
	v_cmp_gt_u32_e32 vcc, v26, v30
	s_bcnt1_i32_b64 s8, vcc
	v_cmp_gt_u32_e32 vcc, v27, v30
	s_bcnt1_i32_b64 s9, vcc
	v_cmp_gt_u32_e32 vcc, v24, v30
	s_bcnt1_i32_b64 s10, vcc
	v_cmp_gt_u32_e32 vcc, v25, v30
	s_add_i32 s8, s8, s9
	s_bcnt1_i32_b64 s11, vcc
	v_cmp_gt_u32_e32 vcc, v22, v30
	s_add_i32 s8, s8, s10
	s_bcnt1_i32_b64 s64, vcc
	v_cmp_gt_u32_e32 vcc, v23, v30
	s_add_i32 s8, s8, s11
	s_bcnt1_i32_b64 s65, vcc
	v_cmp_gt_u32_e32 vcc, v20, v30
	s_add_i32 s8, s8, s64
	s_bcnt1_i32_b64 s66, vcc
	v_cmp_gt_u32_e32 vcc, v21, v30
	s_add_i32 s8, s8, s65
	s_bcnt1_i32_b64 s67, vcc
	v_cmp_gt_u32_e32 vcc, v18, v30
	s_add_i32 s64, s8, s66
	s_bcnt1_i32_b64 s68, vcc
	v_cmp_gt_u32_e32 vcc, v19, v30
	s_add_i32 s64, s64, s67
	s_bcnt1_i32_b64 s69, vcc
	v_cmp_gt_u32_e32 vcc, v14, v30
	s_add_i32 s64, s64, s68
	s_bcnt1_i32_b64 s73, vcc
	v_cmp_gt_u32_e32 vcc, v15, v30
	s_add_i32 s64, s64, s69
	s_bcnt1_i32_b64 s74, vcc
	v_cmp_gt_u32_e32 vcc, v12, v30
	s_add_i32 s64, s64, s73
	s_bcnt1_i32_b64 s75, vcc
	v_cmp_gt_u32_e32 vcc, v13, v30
	s_add_i32 s64, s64, s74
	s_bcnt1_i32_b64 s76, vcc
	v_cmp_gt_u32_e32 vcc, v10, v30
	s_add_i32 s64, s64, s75
	s_bcnt1_i32_b64 s77, vcc
	v_cmp_gt_u32_e32 vcc, v11, v30
	s_add_i32 s64, s64, s76
	s_bcnt1_i32_b64 s78, vcc
	v_cmp_gt_u32_e32 vcc, v8, v30
	s_add_i32 s64, s64, s77
	s_bcnt1_i32_b64 s79, vcc
	v_cmp_gt_u32_e32 vcc, v9, v30
	s_add_i32 s64, s64, s78
	s_bcnt1_i32_b64 s80, vcc
	v_cmp_gt_u32_e32 vcc, v6, v30
	s_add_i32 s64, s64, s79
	s_bcnt1_i32_b64 s81, vcc
	v_cmp_gt_u32_e32 vcc, v7, v30
	s_add_i32 s64, s64, s80
	s_bcnt1_i32_b64 s82, vcc
	v_cmp_gt_u32_e32 vcc, v4, v30
	s_add_i32 s64, s64, s81
	s_bcnt1_i32_b64 s83, vcc
	v_cmp_gt_u32_e32 vcc, v5, v30
	s_add_i32 s64, s64, s82
	s_bcnt1_i32_b64 s84, vcc
	v_cmp_gt_u32_e32 vcc, v2, v30
	s_add_i32 s64, s64, s83
	s_bcnt1_i32_b64 s85, vcc
	v_cmp_gt_u32_e32 vcc, v3, v30
	s_add_i32 s64, s64, s84
	s_bcnt1_i32_b64 s86, vcc
	v_cmp_gt_u32_e32 vcc, v37, v30
	s_add_i32 s64, s64, s85
	s_bcnt1_i32_b64 s87, vcc
	v_cmp_gt_u32_e32 vcc, v36, v30
	s_add_i32 s64, s64, s86
	s_bcnt1_i32_b64 s88, vcc
	v_cmp_gt_u32_e32 vcc, v35, v30
	s_add_i32 s64, s64, s87
	s_bcnt1_i32_b64 s89, vcc
	v_cmp_gt_u32_e32 vcc, v34, v30
	s_add_i32 s64, s64, s88
	s_bcnt1_i32_b64 s90, vcc
	v_cmp_gt_u32_e32 vcc, v33, v30
	s_add_i32 s64, s64, s89
	s_bcnt1_i32_b64 s91, vcc
	v_cmp_gt_u32_e32 vcc, v32, v30
	s_add_i32 s64, s64, s90
	s_bcnt1_i32_b64 s92, vcc
	v_cmp_gt_u32_e32 vcc, v31, v30
	s_add_i32 s64, s64, s91
	s_bcnt1_i32_b64 s93, vcc
	v_cmp_gt_u32_e32 vcc, v29, v30
	s_add_i32 s64, s64, s92
	s_bcnt1_i32_b64 s94, vcc
	s_add_i32 s64, s64, s93
	s_add_i32 s64, s64, s94
	v_cmp_le_u32_e64 s[62:63], v26, v30
	v_cmp_le_u32_e64 s[60:61], v27, v30
	v_cmp_le_u32_e64 s[58:59], v24, v30
	v_cmp_le_u32_e64 s[56:57], v25, v30
	v_cmp_le_u32_e64 s[54:55], v22, v30
	v_cmp_le_u32_e64 s[52:53], v23, v30
	v_cmp_le_u32_e64 s[50:51], v20, v30
	v_cmp_le_u32_e64 s[48:49], v21, v30
	v_cmp_le_u32_e64 s[46:47], v18, v30
	v_cmp_le_u32_e64 s[44:45], v19, v30
	v_cmp_le_u32_e64 s[42:43], v14, v30
	v_cmp_le_u32_e64 s[40:41], v15, v30
	v_cmp_le_u32_e64 s[38:39], v12, v30
	v_cmp_le_u32_e64 s[36:37], v13, v30
	v_cmp_le_u32_e64 s[34:35], v10, v30
	v_cmp_le_u32_e64 s[30:31], v11, v30
	v_cmp_le_u32_e64 s[28:29], v8, v30
	v_cmp_le_u32_e64 s[26:27], v9, v30
	v_cmp_le_u32_e64 s[24:25], v6, v30
	v_cmp_le_u32_e64 s[22:23], v7, v30
	v_cmp_le_u32_e64 s[4:5], v4, v30
	v_cmp_le_u32_e64 s[0:1], v5, v30
	v_cmp_le_u32_e64 s[2:3], v2, v30
	v_cmp_le_u32_e64 s[6:7], v3, v30
	v_cmp_le_u32_e64 s[20:21], v37, v30
	v_cmp_le_u32_e64 s[18:19], v36, v30
	v_cmp_le_u32_e64 s[16:17], v35, v30
	v_cmp_le_u32_e64 s[14:15], v34, v30
	v_cmp_le_u32_e64 s[12:13], v33, v30
	v_cmp_le_u32_e64 s[10:11], v32, v30
	v_cmp_le_u32_e64 s[8:9], v31, v30
	v_cmp_le_u32_e32 vcc, v29, v30
	s_sub_i32 s73, 0x100, s64
	v_cmp_eq_u32_e64 s[64:65], v26, v30
	s_mov_b64 s[68:69], -1
	s_and_saveexec_b64 s[66:67], s[62:63]
	v_mbcnt_lo_u32_b32 v26, s64, 0
	v_mbcnt_hi_u32_b32 v26, s65, v26
	v_cmp_gt_i32_e64 s[62:63], s73, v26
	s_and_b64 s[62:63], s[64:65], s[62:63]
	s_orn2_b64 s[68:69], s[62:63], exec
	s_or_b64 exec, exec, s[66:67]
	v_cndmask_b32_e64 v26, 0, 1, s[68:69]
	v_cmp_eq_u32_e64 s[66:67], 0, v16
	v_cmp_ne_u32_e64 s[68:69], 0, v26
	s_and_saveexec_b64 s[62:63], s[66:67]
	s_cbranch_execz .LBB0_915
	v_mov_b64_e32 v[38:39], s[68:69]
	global_store_dwordx2 v[0:1], v[38:39], off

.LBB0_1044:
	s_mov_b64 s[66:67], 0
	s_mov_b64 s[2:3], 0xf8
	s_cbranch_execz .LBB0_1158
	ds_read2st64_b32 v[18:19], v28 offset1:1
	ds_read2st64_b32 v[14:15], v28 offset0:2 offset1:3
	ds_read2st64_b32 v[12:13], v28 offset0:4 offset1:5
	ds_read2st64_b32 v[10:11], v28 offset0:6 offset1:7
	ds_read2st64_b32 v[8:9], v28 offset0:8 offset1:9
	ds_read2st64_b32 v[6:7], v28 offset0:10 offset1:11
	ds_read2st64_b32 v[4:5], v28 offset0:12 offset1:13
	ds_read2st64_b32 v[2:3], v28 offset0:14 offset1:15
	v_or_b32_e32 v20, 0x400, v16
	v_cmp_gt_u32_e32 vcc, s72, v20
	v_mov_b32_e32 v27, 0
	v_mov_b32_e32 v29, 0
	s_and_saveexec_b64 s[0:1], vcc
	ds_read_b32 v29, v28 offset:4096
	s_or_b64 exec, exec, s[0:1]
	v_or_b32_e32 v20, 0x440, v16
	v_cmp_gt_u32_e32 vcc, s72, v20
	s_and_saveexec_b64 s[0:1], vcc
	ds_read_b32 v27, v28 offset:4352
	s_or_b64 exec, exec, s[0:1]
	v_or_b32_e32 v20, 0x480, v16
	v_cmp_gt_u32_e32 vcc, s72, v20
	v_mov_b32_e32 v25, 0
	v_mov_b32_e32 v26, 0
	s_and_saveexec_b64 s[0:1], vcc
	ds_read_b32 v26, v28 offset:4608
	s_or_b64 exec, exec, s[0:1]
	v_or_b32_e32 v20, 0x4c0, v16
	v_cmp_gt_u32_e32 vcc, s72, v20
	s_and_saveexec_b64 s[0:1], vcc
	ds_read_b32 v25, v28 offset:4864
	s_or_b64 exec, exec, s[0:1]
	v_or_b32_e32 v20, 0x500, v16
	v_cmp_gt_u32_e32 vcc, s72, v20
	v_mov_b32_e32 v23, 0
	v_mov_b32_e32 v24, 0
	s_and_saveexec_b64 s[0:1], vcc
	ds_read_b32 v24, v28 offset:5120
	s_or_b64 exec, exec, s[0:1]
	v_or_b32_e32 v20, 0x540, v16
	v_cmp_gt_u32_e32 vcc, s72, v20
	s_and_saveexec_b64 s[0:1], vcc
	ds_read_b32 v23, v28 offset:5376
	s_or_b64 exec, exec, s[0:1]
	v_or_b32_e32 v20, 0x580, v16
	v_cmp_gt_u32_e32 vcc, s72, v20
	v_mov_b32_e32 v20, 0
	v_mov_b32_e32 v22, 0
	s_and_saveexec_b64 s[0:1], vcc
	ds_read_b32 v22, v28 offset:5632
	s_or_b64 exec, exec, s[0:1]
	v_or_b32_e32 v21, 0x5c0, v16
	v_cmp_gt_u32_e32 vcc, s72, v21
	s_and_saveexec_b64 s[0:1], vcc
	ds_read_b32 v20, v28 offset:5888
	s_or_b64 exec, exec, s[0:1]
	s_waitcnt vmcnt(2)
	v_mov_b32_e32 v30, 31
	v_mov_b32_e32 v21, 0
	s_waitcnt lgkmcnt(0)
	s_waitcnt vmcnt(0)
	v_max_u32_e32 v138, v18, v8
	v_min_u32_e32 v139, v18, v8
	v_max_u32_e32 v140, v19, v9
	v_min_u32_e32 v141, v19, v9
	v_max_u32_e32 v142, v14, v6
	v_min_u32_e32 v143, v14, v6
	v_max_u32_e32 v144, v15, v7
	v_min_u32_e32 v145, v15, v7
	v_max_u32_e32 v146, v12, v4
	v_min_u32_e32 v147, v12, v4
	v_max_u32_e32 v148, v13, v5
	v_min_u32_e32 v149, v13, v5
	v_max_u32_e32 v150, v10, v2
	v_min_u32_e32 v151, v10, v2
	v_max_u32_e32 v152, v11, v3
	v_min_u32_e32 v153, v11, v3
	v_max_u32_e32 v154, v138, v146
	v_min_u32_e32 v155, v138, v146
	v_max_u32_e32 v146, v140, v148
	v_min_u32_e32 v138, v140, v148
	v_max_u32_e32 v148, v142, v150
	v_min_u32_e32 v140, v142, v150
	v_max_u32_e32 v150, v144, v152
	v_min_u32_e32 v142, v144, v152
	v_max_u32_e32 v152, v139, v147
	v_min_u32_e32 v144, v139, v147
	v_max_u32_e32 v147, v141, v149
	v_min_u32_e32 v139, v141, v149
	v_max_u32_e32 v149, v143, v151
	v_min_u32_e32 v141, v143, v151
	v_max_u32_e32 v151, v145, v153
	v_min_u32_e32 v143, v145, v153
	v_max_u32_e32 v153, v155, v152
	v_min_u32_e32 v145, v155, v152
	v_max_u32_e32 v152, v138, v147
	v_min_u32_e32 v155, v138, v147
	v_max_u32_e32 v147, v140, v149
	v_min_u32_e32 v138, v140, v149
	v_max_u32_e32 v149, v142, v151
	v_min_u32_e32 v140, v142, v151
	v_max_u32_e32 v151, v154, v148
	v_min_u32_e32 v142, v154, v148
	v_max_u32_e32 v148, v146, v150
	v_min_u32_e32 v154, v146, v150
	v_max_u32_e32 v150, v153, v147
	v_min_u32_e32 v146, v153, v147
	v_max_u32_e32 v147, v152, v149
	v_min_u32_e32 v153, v152, v149
	v_max_u32_e32 v149, v145, v138
	v_min_u32_e32 v152, v145, v138
	v_max_u32_e32 v138, v155, v140
	v_min_u32_e32 v145, v155, v140
	v_max_u32_e32 v140, v144, v141
	v_min_u32_e32 v155, v144, v141
	v_max_u32_e32 v141, v139, v143
	v_min_u32_e32 v144, v139, v143
	v_max_u32_e32 v143, v142, v149
	v_min_u32_e32 v139, v142, v149
	v_max_u32_e32 v149, v154, v138
	v_min_u32_e32 v142, v154, v138
	v_max_u32_e32 v138, v146, v140
	v_min_u32_e32 v154, v146, v140
	v_max_u32_e32 v140, v153, v141
	v_min_u32_e32 v146, v153, v141
	v_max_u32_e32 v141, v143, v150
	v_min_u32_e32 v153, v143, v150
	v_max_u32_e32 v150, v149, v147
	v_min_u32_e32 v143, v149, v147
	v_max_u32_e32 v147, v138, v139
	v_min_u32_e32 v149, v138, v139
	v_max_u32_e32 v139, v140, v142
	v_min_u32_e32 v138, v140, v142
	v_max_u32_e32 v142, v152, v154
	v_min_u32_e32 v140, v152, v154
	v_max_u32_e32 v154, v145, v146
	v_min_u32_e32 v152, v145, v146
	v_max_u32_e32 v146, v151, v148
	v_min_u32_e32 v145, v151, v148
	v_max_u32_e32 v148, v141, v150
	v_min_u32_e32 v151, v141, v150
	v_max_u32_e32 v150, v153, v143
	v_min_u32_e32 v141, v153, v143
	v_max_u32_e32 v143, v147, v139
	v_min_u32_e32 v153, v147, v139
	v_max_u32_e32 v139, v149, v138
	v_min_u32_e32 v147, v149, v138
	v_max_u32_e32 v138, v142, v154
	v_min_u32_e32 v149, v142, v154
	v_max_u32_e32 v154, v140, v152
	v_min_u32_e32 v142, v140, v152
	v_max_u32_e32 v152, v155, v144
	v_min_u32_e32 v140, v155, v144
	v_max_u32_e32 v144, v145, v139
	v_min_u32_e32 v155, v145, v139
	v_max_u32_e32 v139, v151, v138
	v_min_u32_e32 v145, v151, v138
	v_max_u32_e32 v138, v141, v154
	v_min_u32_e32 v151, v141, v154
	v_max_u32_e32 v154, v153, v152
	v_min_u32_e32 v141, v153, v152
	v_max_u32_e32 v152, v144, v150
	v_min_u32_e32 v153, v144, v150
	v_max_u32_e32 v150, v139, v143
	v_min_u32_e32 v144, v139, v143
	v_max_u32_e32 v143, v138, v155
	v_min_u32_e32 v139, v138, v155
	v_max_u32_e32 v155, v154, v145
	v_min_u32_e32 v138, v154, v145
	v_max_u32_e32 v145, v147, v151
	v_min_u32_e32 v154, v147, v151
	v_max_u32_e32 v151, v149, v141
	v_min_u32_e32 v147, v149, v141
	v_max_u32_e32 v141, v152, v148
	v_min_u32_e32 v149, v152, v148
	v_max_u32_e32 v148, v150, v153
	v_min_u32_e32 v152, v150, v153
	v_max_u32_e32 v153, v143, v144
	v_min_u32_e32 v150, v143, v144
	v_max_u32_e32 v144, v155, v139
	v_min_u32_e32 v143, v155, v139
	v_max_u32_e32 v139, v145, v138
	v_min_u32_e32 v155, v145, v138
	v_max_u32_e32 v138, v151, v154
	v_min_u32_e32 v145, v151, v154
	v_max_u32_e32 v154, v142, v147
	v_min_u32_e32 v151, v142, v147
	v_max_u32_e32 v147, v29, v24
	v_min_u32_e32 v142, v29, v24
	v_max_u32_e32 v156, v27, v23
	v_min_u32_e32 v157, v27, v23
	v_max_u32_e32 v158, v26, v22
	v_min_u32_e32 v159, v26, v22
	v_max_u32_e32 v160, v25, v20
	v_min_u32_e32 v161, v25, v20
	v_max_u32_e32 v162, v147, v158
	v_min_u32_e32 v163, v147, v158
	v_max_u32_e32 v158, v156, v160
	v_min_u32_e32 v147, v156, v160
	v_max_u32_e32 v160, v142, v159
	v_min_u32_e32 v156, v142, v159
	v_max_u32_e32 v159, v157, v161
	v_min_u32_e32 v142, v157, v161
	v_max_u32_e32 v161, v163, v160
	v_min_u32_e32 v157, v163, v160
	v_max_u32_e32 v160, v147, v159
	v_min_u32_e32 v163, v147, v159
	v_max_u32_e32 v159, v162, v158
	v_min_u32_e32 v147, v162, v158
	v_max_u32_e32 v158, v161, v160
	v_min_u32_e32 v162, v161, v160
	v_max_u32_e32 v160, v157, v163
	v_min_u32_e32 v161, v157, v163
	v_max_u32_e32 v163, v156, v142
	v_min_u32_e32 v157, v156, v142
	v_max_u32_e32 v142, v147, v160
	v_min_u32_e32 v156, v147, v160
	v_max_u32_e32 v160, v162, v163
	v_min_u32_e32 v147, v162, v163
	v_max_u32_e32 v163, v142, v158
	v_min_u32_e32 v162, v142, v158
	v_max_u32_e32 v158, v160, v156
	v_min_u32_e32 v142, v160, v156
	v_max_u32_e32 v156, v161, v147
	v_min_u32_e32 v160, v161, v147
.LBB0_1062:
	v_lshlrev_b32_e64 v31, v30, 1
	v_or_b32_e32 v31, v31, v21
	v_cmp_ge_u32_e64 s[48:49], v144, v31
	v_cmp_ge_u32_e64 s[100:101], v140, v31
	s_nop 0
	v_cndmask_b32_e64 v134, v148, v138, s[48:49]
	v_cmp_ge_u32_e64 s[50:51], v134, v31
	s_nop 1
	v_cndmask_b32_e64 v134, v141, v153, s[50:51]
	v_cndmask_b32_e64 v135, v139, v154, s[50:51]
	v_cndmask_b32_e64 v134, v134, v135, s[48:49]
	v_cmp_ge_u32_e64 s[52:53], v134, v31
	s_nop 1
	v_cndmask_b32_e64 v134, v146, v149, s[52:53]
	v_cndmask_b32_e64 v135, v152, v150, s[52:53]
	v_cndmask_b32_e64 v136, v143, v155, s[52:53]
	v_cndmask_b32_e64 v137, v145, v151, s[52:53]
	v_cndmask_b32_e64 v134, v134, v135, s[50:51]
	v_cndmask_b32_e64 v136, v136, v137, s[50:51]
	v_cndmask_b32_e64 v134, v134, v136, s[48:49]
	v_cmp_ge_u32_e64 s[98:99], v134, v31
	s_bcnt1_i32_b64 s1, s[48:49]
	s_mov_b32 s0, s1
	s_bcnt1_i32_b64 s1, s[50:51]
	s_lshl1_add_u32 s0, s0, s1
	s_bcnt1_i32_b64 s1, s[52:53]
	s_lshl1_add_u32 s0, s0, s1
	s_bcnt1_i32_b64 s1, s[98:99]
	s_lshl1_add_u32 s0, s0, s1
	s_bcnt1_i32_b64 s1, s[100:101]
	s_add_i32 s0, s0, s1
	s_mov_b32 s2, s0
	v_cmp_ge_u32_e64 s[48:49], v158, v31
	v_cmp_ge_u32_e64 s[98:99], v157, v31
	s_nop 0
	v_cndmask_b32_e64 v134, v163, v156, s[48:49]
	v_cmp_ge_u32_e64 s[50:51], v134, v31
	s_nop 1
	v_cndmask_b32_e64 v134, v159, v162, s[50:51]
	v_cndmask_b32_e64 v135, v142, v160, s[50:51]
	v_cndmask_b32_e64 v134, v134, v135, s[48:49]
	v_cmp_ge_u32_e64 s[52:53], v134, v31
	s_bcnt1_i32_b64 s1, s[48:49]
	s_mov_b32 s0, s1
	s_bcnt1_i32_b64 s1, s[50:51]
	s_lshl1_add_u32 s0, s0, s1
	s_bcnt1_i32_b64 s1, s[52:53]
	s_lshl1_add_u32 s0, s0, s1
	s_bcnt1_i32_b64 s1, s[98:99]
	s_add_i32 s0, s0, s1
	s_add_i32 s2, s2, s0
	s_cmpk_eq_i32 s2, 0x100
	s_cselect_b64 s[0:1], -1, 0
	s_cmpk_lt_u32 s2, 0x100
	s_cselect_b64 vcc, -1, 0
	v_cndmask_b32_e32 v21, v31, v21, vcc
	v_subrev_co_u32_e32 v30, vcc, 1, v30
	s_or_b64 s[0:1], s[0:1], vcc
	s_andn2_b64 vcc, exec, s[0:1]
	s_cbranch_vccnz .LBB0_1062
	s_cmpk_eq_i32 s2, 0x100
	s_cbranch_scc1 .Lselfast_24
	v_cmp_gt_u32_e32 vcc, v18, v21
	s_bcnt1_i32_b64 s50, vcc
	v_cmp_gt_u32_e32 vcc, v19, v21
	s_bcnt1_i32_b64 s51, vcc
	v_cmp_gt_u32_e32 vcc, v14, v21
	v_cmp_gt_u32_e64 s[48:49], v20, v21
	s_bcnt1_i32_b64 s52, vcc
	v_cmp_gt_u32_e32 vcc, v15, v21
	s_bcnt1_i32_b64 s48, s[48:49]
	s_add_i32 s49, s50, s51
	s_bcnt1_i32_b64 s53, vcc
	v_cmp_gt_u32_e32 vcc, v12, v21
	s_add_i32 s49, s49, s52
	s_bcnt1_i32_b64 s54, vcc
	v_cmp_gt_u32_e32 vcc, v13, v21
	s_add_i32 s49, s49, s53
	s_bcnt1_i32_b64 s55, vcc
	v_cmp_gt_u32_e32 vcc, v10, v21
	s_add_i32 s49, s49, s54
	s_bcnt1_i32_b64 s56, vcc
	v_cmp_gt_u32_e32 vcc, v11, v21
	s_add_i32 s49, s49, s55
	s_bcnt1_i32_b64 s57, vcc
	v_cmp_gt_u32_e32 vcc, v8, v21
	s_add_i32 s49, s49, s56
	s_bcnt1_i32_b64 s58, vcc
	v_cmp_gt_u32_e32 vcc, v9, v21
	s_add_i32 s49, s49, s57
	s_bcnt1_i32_b64 s59, vcc
	v_cmp_gt_u32_e32 vcc, v6, v21
	s_add_i32 s49, s49, s58
	s_bcnt1_i32_b64 s60, vcc
	v_cmp_gt_u32_e32 vcc, v7, v21
	s_add_i32 s49, s49, s59
	s_bcnt1_i32_b64 s61, vcc
	v_cmp_gt_u32_e32 vcc, v4, v21
	s_add_i32 s49, s49, s60
	s_bcnt1_i32_b64 s62, vcc
	v_cmp_gt_u32_e32 vcc, v5, v21
	s_add_i32 s49, s49, s61
	s_bcnt1_i32_b64 s63, vcc
	v_cmp_gt_u32_e32 vcc, v2, v21
	s_add_i32 s49, s49, s62
	s_bcnt1_i32_b64 s64, vcc
	v_cmp_gt_u32_e32 vcc, v3, v21
	s_add_i32 s49, s49, s63
	s_bcnt1_i32_b64 s65, vcc
	v_cmp_gt_u32_e32 vcc, v29, v21
	s_add_i32 s49, s49, s64
	s_bcnt1_i32_b64 s66, vcc
	v_cmp_gt_u32_e32 vcc, v27, v21
	s_add_i32 s49, s49, s65
	s_bcnt1_i32_b64 s67, vcc
	v_cmp_gt_u32_e32 vcc, v26, v21
	s_add_i32 s49, s49, s66
	s_bcnt1_i32_b64 s68, vcc
	v_cmp_gt_u32_e32 vcc, v25, v21
	s_add_i32 s49, s49, s67
	s_bcnt1_i32_b64 s69, vcc
	v_cmp_gt_u32_e32 vcc, v24, v21
	s_add_i32 s49, s49, s68
	s_bcnt1_i32_b64 s73, vcc
	v_cmp_gt_u32_e32 vcc, v23, v21
	s_add_i32 s49, s49, s69
	s_bcnt1_i32_b64 s74, vcc
	v_cmp_gt_u32_e32 vcc, v22, v21
	s_add_i32 s49, s49, s73
	s_bcnt1_i32_b64 s75, vcc
	s_add_i32 s49, s49, s74
	s_add_i32 s49, s49, s75
	s_add_i32 s49, s49, s48
	v_cmp_le_u32_e64 s[46:47], v18, v21
	v_cmp_le_u32_e64 s[44:45], v19, v21
	v_cmp_le_u32_e64 s[42:43], v14, v21
	v_cmp_le_u32_e64 s[40:41], v15, v21
	v_cmp_le_u32_e64 s[38:39], v12, v21
	v_cmp_le_u32_e64 s[36:37], v13, v21
	v_cmp_le_u32_e64 s[34:35], v10, v21
	v_cmp_le_u32_e64 s[30:31], v11, v21
	v_cmp_le_u32_e64 s[28:29], v8, v21
	v_cmp_le_u32_e64 s[26:27], v9, v21
	v_cmp_le_u32_e64 s[24:25], v6, v21
	v_cmp_le_u32_e64 s[22:23], v7, v21
	v_cmp_le_u32_e64 s[20:21], v4, v21
	v_cmp_le_u32_e64 s[18:19], v5, v21
	v_cmp_le_u32_e64 s[16:17], v2, v21
	v_cmp_le_u32_e64 s[14:15], v3, v21
	v_cmp_le_u32_e64 s[12:13], v29, v21
	v_cmp_le_u32_e64 s[10:11], v27, v21
	v_cmp_le_u32_e64 s[8:9], v26, v21
	v_cmp_le_u32_e64 s[6:7], v25, v21
	v_cmp_le_u32_e64 s[4:5], v24, v21
	v_cmp_le_u32_e64 s[2:3], v23, v21
	v_cmp_le_u32_e64 s[0:1], v22, v21
	v_cmp_le_u32_e32 vcc, v20, v21
	s_sub_i32 s54, 0x100, s49
	v_cmp_eq_u32_e64 s[48:49], v18, v21
	s_mov_b64 s[52:53], -1
	s_and_saveexec_b64 s[50:51], s[46:47]
	v_mbcnt_lo_u32_b32 v18, s48, 0
	v_mbcnt_hi_u32_b32 v18, s49, v18
	v_cmp_gt_i32_e64 s[46:47], s54, v18
	s_and_b64 s[46:47], s[48:49], s[46:47]
	s_orn2_b64 s[52:53], s[46:47], exec
	s_or_b64 exec, exec, s[50:51]
	v_cndmask_b32_e64 v18, 0, 1, s[52:53]
	v_cmp_eq_u32_e64 s[66:67], 0, v16
	v_cmp_ne_u32_e64 s[50:51], 0, v18
	s_and_saveexec_b64 s[46:47], s[66:67]
	s_cbranch_execz .LBB0_1067
	v_mov_b64_e32 v[30:31], s[50:51]
	global_store_dwordx2 v[0:1], v[30:31], off

.LBB0_1159:
	ds_read2st64_b32 v[8:9], v28 offset1:1
	ds_read2st64_b32 v[6:7], v28 offset0:2 offset1:3
	ds_read2st64_b32 v[4:5], v28 offset0:4 offset1:5
	ds_read2st64_b32 v[2:3], v28 offset0:6 offset1:7
	v_or_b32_e32 v10, 0x200, v16
	v_cmp_gt_u32_e32 vcc, s72, v10
	v_mov_b32_e32 v19, 0
	v_mov_b32_e32 v20, 0
	s_and_saveexec_b64 s[0:1], vcc
	ds_read_b32 v20, v28 offset:2048
	s_or_b64 exec, exec, s[0:1]
	v_or_b32_e32 v10, 0x240, v16
	v_cmp_gt_u32_e32 vcc, s72, v10
	s_and_saveexec_b64 s[0:1], vcc
	ds_read_b32 v19, v28 offset:2304
	s_or_b64 exec, exec, s[0:1]
	v_or_b32_e32 v10, 0x280, v16
	v_cmp_gt_u32_e32 vcc, s72, v10
	v_mov_b32_e32 v15, 0
	v_mov_b32_e32 v18, 0
	s_and_saveexec_b64 s[0:1], vcc
	ds_read_b32 v18, v28 offset:2560
	s_or_b64 exec, exec, s[0:1]
	v_or_b32_e32 v10, 0x2c0, v16
	v_cmp_gt_u32_e32 vcc, s72, v10
	s_and_saveexec_b64 s[0:1], vcc
	ds_read_b32 v15, v28 offset:2816
	s_or_b64 exec, exec, s[0:1]
	v_or_b32_e32 v10, 0x300, v16
	v_cmp_gt_u32_e32 vcc, s72, v10
	v_mov_b32_e32 v13, 0
	v_mov_b32_e32 v14, 0
	s_and_saveexec_b64 s[0:1], vcc
	ds_read_b32 v14, v28 offset:3072
	s_or_b64 exec, exec, s[0:1]
	v_or_b32_e32 v10, 0x340, v16
	v_cmp_gt_u32_e32 vcc, s72, v10
	s_and_saveexec_b64 s[0:1], vcc
	ds_read_b32 v13, v28 offset:3328
	s_or_b64 exec, exec, s[0:1]
	v_or_b32_e32 v10, 0x380, v16
	v_cmp_gt_u32_e32 vcc, s72, v10
	v_mov_b32_e32 v10, 0
	v_mov_b32_e32 v12, 0
	s_and_saveexec_b64 s[0:1], vcc
	ds_read_b32 v12, v28 offset:3584
	s_or_b64 exec, exec, s[0:1]
	v_or_b32_e32 v11, 0x3c0, v16
	v_cmp_gt_u32_e32 vcc, s72, v11
	s_and_saveexec_b64 s[0:1], vcc
	ds_read_b32 v10, v28 offset:3840
	s_or_b64 exec, exec, s[0:1]
	v_mov_b32_e32 v21, 31
	v_mov_b32_e32 v11, 0
	s_waitcnt lgkmcnt(0)
	s_waitcnt vmcnt(0)
	v_max_u32_e32 v138, v8, v20
	v_min_u32_e32 v139, v8, v20
	v_max_u32_e32 v140, v9, v19
	v_min_u32_e32 v141, v9, v19
	v_max_u32_e32 v142, v6, v18
	v_min_u32_e32 v143, v6, v18
	v_max_u32_e32 v144, v7, v15
	v_min_u32_e32 v145, v7, v15
	v_max_u32_e32 v146, v4, v14
	v_min_u32_e32 v147, v4, v14
	v_max_u32_e32 v148, v5, v13
	v_min_u32_e32 v149, v5, v13
	v_max_u32_e32 v150, v2, v12
	v_min_u32_e32 v151, v2, v12
	v_max_u32_e32 v152, v3, v10
	v_min_u32_e32 v153, v3, v10
	v_max_u32_e32 v154, v138, v146
	v_min_u32_e32 v155, v138, v146
	v_max_u32_e32 v146, v140, v148
	v_min_u32_e32 v138, v140, v148
	v_max_u32_e32 v148, v142, v150
	v_min_u32_e32 v140, v142, v150
	v_max_u32_e32 v150, v144, v152
	v_min_u32_e32 v142, v144, v152
	v_max_u32_e32 v152, v139, v147
	v_min_u32_e32 v144, v139, v147
	v_max_u32_e32 v147, v141, v149
	v_min_u32_e32 v139, v141, v149
	v_max_u32_e32 v149, v143, v151
	v_min_u32_e32 v141, v143, v151
	v_max_u32_e32 v151, v145, v153
	v_min_u32_e32 v143, v145, v153
	v_max_u32_e32 v153, v155, v152
	v_min_u32_e32 v145, v155, v152
	v_max_u32_e32 v152, v138, v147
	v_min_u32_e32 v155, v138, v147
	v_max_u32_e32 v147, v140, v149
	v_min_u32_e32 v138, v140, v149
	v_max_u32_e32 v149, v142, v151
	v_min_u32_e32 v140, v142, v151
	v_max_u32_e32 v151, v154, v148
	v_min_u32_e32 v142, v154, v148
	v_max_u32_e32 v148, v146, v150
	v_min_u32_e32 v154, v146, v150
	v_max_u32_e32 v150, v153, v147
	v_min_u32_e32 v146, v153, v147
	v_max_u32_e32 v147, v152, v149
	v_min_u32_e32 v153, v152, v149
	v_max_u32_e32 v149, v145, v138
	v_min_u32_e32 v152, v145, v138
	v_max_u32_e32 v138, v155, v140
	v_min_u32_e32 v145, v155, v140
	v_max_u32_e32 v140, v144, v141
	v_min_u32_e32 v155, v144, v141
	v_max_u32_e32 v141, v139, v143
	v_min_u32_e32 v144, v139, v143
	v_max_u32_e32 v143, v142, v149
	v_min_u32_e32 v139, v142, v149
	v_max_u32_e32 v149, v154, v138
	v_min_u32_e32 v142, v154, v138
	v_max_u32_e32 v138, v146, v140
	v_min_u32_e32 v154, v146, v140
	v_max_u32_e32 v140, v153, v141
	v_min_u32_e32 v146, v153, v141
	v_max_u32_e32 v141, v143, v150
	v_min_u32_e32 v153, v143, v150
	v_max_u32_e32 v150, v149, v147
	v_min_u32_e32 v143, v149, v147
	v_max_u32_e32 v147, v138, v139
	v_min_u32_e32 v149, v138, v139
	v_max_u32_e32 v139, v140, v142
	v_min_u32_e32 v138, v140, v142
	v_max_u32_e32 v142, v152, v154
	v_min_u32_e32 v140, v152, v154
	v_max_u32_e32 v154, v145, v146
	v_min_u32_e32 v152, v145, v146
	v_max_u32_e32 v146, v151, v148
	v_min_u32_e32 v145, v151, v148
	v_max_u32_e32 v148, v141, v150
	v_min_u32_e32 v151, v141, v150
	v_max_u32_e32 v150, v153, v143
	v_min_u32_e32 v141, v153, v143
	v_max_u32_e32 v143, v147, v139
	v_min_u32_e32 v153, v147, v139
	v_max_u32_e32 v139, v149, v138
	v_min_u32_e32 v147, v149, v138
	v_max_u32_e32 v138, v142, v154
	v_min_u32_e32 v149, v142, v154
	v_max_u32_e32 v154, v140, v152
	v_min_u32_e32 v142, v140, v152
	v_max_u32_e32 v152, v155, v144
	v_min_u32_e32 v140, v155, v144
	v_max_u32_e32 v144, v145, v139
	v_min_u32_e32 v155, v145, v139
	v_max_u32_e32 v139, v151, v138
	v_min_u32_e32 v145, v151, v138
	v_max_u32_e32 v138, v141, v154
	v_min_u32_e32 v151, v141, v154
	v_max_u32_e32 v154, v153, v152
	v_min_u32_e32 v141, v153, v152
	v_max_u32_e32 v152, v144, v150
	v_min_u32_e32 v153, v144, v150
	v_max_u32_e32 v150, v139, v143
	v_min_u32_e32 v144, v139, v143
	v_max_u32_e32 v143, v138, v155
	v_min_u32_e32 v139, v138, v155
	v_max_u32_e32 v155, v154, v145
	v_min_u32_e32 v138, v154, v145
	v_max_u32_e32 v145, v147, v151
	v_min_u32_e32 v154, v147, v151
	v_max_u32_e32 v151, v149, v141
	v_min_u32_e32 v147, v149, v141
	v_max_u32_e32 v141, v152, v148
	v_min_u32_e32 v149, v152, v148
	v_max_u32_e32 v148, v150, v153
	v_min_u32_e32 v152, v150, v153
	v_max_u32_e32 v153, v143, v144
	v_min_u32_e32 v150, v143, v144
	v_max_u32_e32 v144, v155, v139
	v_min_u32_e32 v143, v155, v139
	v_max_u32_e32 v139, v145, v138
	v_min_u32_e32 v155, v145, v138
	v_max_u32_e32 v138, v151, v154
	v_min_u32_e32 v145, v151, v154
	v_max_u32_e32 v154, v142, v147
	v_min_u32_e32 v151, v142, v147
.LBB0_1176:
	v_lshlrev_b32_e64 v22, v21, 1
	v_or_b32_e32 v22, v22, v11
	v_cmp_ge_u32_e64 s[28:29], v144, v22
	v_cmp_ge_u32_e64 s[100:101], v140, v22
	s_nop 0
	v_cndmask_b32_e64 v134, v148, v138, s[28:29]
	v_cmp_ge_u32_e64 s[34:35], v134, v22
	s_nop 1
	v_cndmask_b32_e64 v134, v141, v153, s[34:35]
	v_cndmask_b32_e64 v135, v139, v154, s[34:35]
	v_cndmask_b32_e64 v134, v134, v135, s[28:29]
	v_cmp_ge_u32_e64 s[36:37], v134, v22
	s_nop 1
	v_cndmask_b32_e64 v134, v146, v149, s[36:37]
	v_cndmask_b32_e64 v135, v152, v150, s[36:37]
	v_cndmask_b32_e64 v136, v143, v155, s[36:37]
	v_cndmask_b32_e64 v137, v145, v151, s[36:37]
	v_cndmask_b32_e64 v134, v134, v135, s[34:35]
	v_cndmask_b32_e64 v136, v136, v137, s[34:35]
	v_cndmask_b32_e64 v134, v134, v136, s[28:29]
	v_cmp_ge_u32_e64 s[98:99], v134, v22
	s_bcnt1_i32_b64 s1, s[28:29]
	s_mov_b32 s0, s1
	s_bcnt1_i32_b64 s1, s[34:35]
	s_lshl1_add_u32 s0, s0, s1
	s_bcnt1_i32_b64 s1, s[36:37]
	s_lshl1_add_u32 s0, s0, s1
	s_bcnt1_i32_b64 s1, s[98:99]
	s_lshl1_add_u32 s0, s0, s1
	s_bcnt1_i32_b64 s1, s[100:101]
	s_add_i32 s0, s0, s1
	s_mov_b32 s2, s0
	s_cmpk_eq_i32 s2, 0x100
	s_cselect_b64 s[0:1], -1, 0
	s_cmpk_lt_u32 s2, 0x100
	s_cselect_b64 vcc, -1, 0
	v_cndmask_b32_e32 v11, v22, v11, vcc
	v_subrev_co_u32_e32 v21, vcc, 1, v21
	s_or_b64 s[0:1], s[0:1], vcc
	s_andn2_b64 vcc, exec, s[0:1]
	s_cbranch_vccnz .LBB0_1176
	s_cmpk_eq_i32 s2, 0x100
	s_cbranch_scc1 .Lselfast_16
	v_cmp_gt_u32_e32 vcc, v8, v11
	s_bcnt1_i32_b64 s34, vcc
	v_cmp_gt_u32_e32 vcc, v9, v11
	s_bcnt1_i32_b64 s35, vcc
	v_cmp_gt_u32_e32 vcc, v6, v11
	v_cmp_gt_u32_e64 s[28:29], v10, v11
	s_bcnt1_i32_b64 s36, vcc
	v_cmp_gt_u32_e32 vcc, v7, v11
	s_bcnt1_i32_b64 s28, s[28:29]
	s_add_i32 s29, s34, s35
	s_bcnt1_i32_b64 s37, vcc
	v_cmp_gt_u32_e32 vcc, v4, v11
	s_add_i32 s29, s29, s36
	s_bcnt1_i32_b64 s38, vcc
	v_cmp_gt_u32_e32 vcc, v5, v11
	s_add_i32 s29, s29, s37
	s_bcnt1_i32_b64 s39, vcc
	v_cmp_gt_u32_e32 vcc, v2, v11
	s_add_i32 s29, s29, s38
	s_bcnt1_i32_b64 s40, vcc
	v_cmp_gt_u32_e32 vcc, v3, v11
	s_add_i32 s29, s29, s39
	s_bcnt1_i32_b64 s41, vcc
	v_cmp_gt_u32_e32 vcc, v20, v11
	s_add_i32 s29, s29, s40
	s_bcnt1_i32_b64 s42, vcc
	v_cmp_gt_u32_e32 vcc, v19, v11
	s_add_i32 s29, s29, s41
	s_bcnt1_i32_b64 s43, vcc
	v_cmp_gt_u32_e32 vcc, v18, v11
	s_add_i32 s29, s29, s42
	s_bcnt1_i32_b64 s44, vcc
	v_cmp_gt_u32_e32 vcc, v15, v11
	s_add_i32 s29, s29, s43
	s_bcnt1_i32_b64 s45, vcc
	v_cmp_gt_u32_e32 vcc, v14, v11
	s_add_i32 s29, s29, s44
	s_bcnt1_i32_b64 s46, vcc
	v_cmp_gt_u32_e32 vcc, v13, v11
	s_add_i32 s29, s29, s45
	s_bcnt1_i32_b64 s47, vcc
	v_cmp_gt_u32_e32 vcc, v12, v11
	s_add_i32 s29, s29, s46
	s_bcnt1_i32_b64 s48, vcc
	s_add_i32 s29, s29, s47
	s_add_i32 s29, s29, s48
	s_add_i32 s29, s29, s28
	v_cmp_le_u32_e64 s[30:31], v8, v11
	v_cmp_le_u32_e64 s[26:27], v9, v11
	v_cmp_le_u32_e64 s[24:25], v6, v11
	v_cmp_le_u32_e64 s[22:23], v7, v11
	v_cmp_le_u32_e64 s[20:21], v4, v11
	v_cmp_le_u32_e64 s[18:19], v5, v11
	v_cmp_le_u32_e64 s[16:17], v2, v11
	v_cmp_le_u32_e64 s[14:15], v3, v11
	v_cmp_le_u32_e64 s[12:13], v20, v11
	v_cmp_le_u32_e64 s[10:11], v19, v11
	v_cmp_le_u32_e64 s[8:9], v18, v11
	v_cmp_le_u32_e64 s[6:7], v15, v11
	v_cmp_le_u32_e64 s[4:5], v14, v11
	v_cmp_le_u32_e64 s[2:3], v13, v11
	v_cmp_le_u32_e64 s[0:1], v12, v11
	v_cmp_le_u32_e32 vcc, v10, v11
	s_sub_i32 s38, 0x100, s29
	v_cmp_eq_u32_e64 s[28:29], v8, v11
	s_mov_b64 s[36:37], -1
	s_and_saveexec_b64 s[34:35], s[30:31]
	v_mbcnt_lo_u32_b32 v8, s28, 0
	v_mbcnt_hi_u32_b32 v8, s29, v8
	v_cmp_gt_i32_e64 s[30:31], s38, v8
	s_and_b64 s[30:31], s[28:29], s[30:31]
	s_orn2_b64 s[36:37], s[30:31], exec
	s_or_b64 exec, exec, s[34:35]
	v_cndmask_b32_e64 v8, 0, 1, s[36:37]
	v_cmp_eq_u32_e64 s[66:67], 0, v16
	v_cmp_ne_u32_e64 s[34:35], 0, v8
	s_and_saveexec_b64 s[30:31], s[66:67]
	s_cbranch_execz .LBB0_1181
	v_mov_b64_e32 v[22:23], s[34:35]
	global_store_dwordx2 v[0:1], v[22:23], off
